# attention loop re-pipelined: V-fragment reads hoisted, softmax partial under P.V MFMAs, DMA address SALU woven into QK MFMAs
# speedup vs baseline: 1.0123x; 1.0123x over previous
; __device__ __forceinline__ void finishSM(f32x16& p0, f32x16& p1, float alpha, float& l_reg, bf16x8& pa0, bf16x8& pa1, bf16x8& pa2, bf16x8& pa3) {
;   for (int r = 0; r < 16; ++r) p1[r] = __builtin_amdgcn_exp2f(p1[r]);
;   float ps = 0; for (int r = 0; r < 16; ++r) ps += p0[r]; for (int r = 0; r < 16; ++r) ps += p1[r];
;   { auto rr = __builtin_amdgcn_permlane32_swap(__float_as_uint(ps), __float_as_uint(ps), false, false);
;     ps = __uint_as_float(rr[0]) + __uint_as_float(rr[1]); }
;   l_reg = l_reg * alpha + ps;
;     ...
;   PK4(p0, 0, pa0); PK4(p0, 8, pa1); PK4(p1, 0, pa2); PK4(p1, 8, pa3);
;     ...
; }
; __device__ __forceinline__ void kload(bf16x8 (&kf)[8], const char* Ks, int r32, int hi, int sb) {
; #pragma unroll
;   for (int d0 = 0; d0 < 4; ++d0) { const int cb = sb + (d0 * 16 + hi * 8) * 2;
;     kf[2 * d0] = *reinterpret_cast<const bf16x8*>(Ks + KSWZ(r32, cb)); kf[2 * d0 + 1] = *reinterpret_cast<const bf16x8*>(Ks + KSWZ(32 + r32, cb)); }
; }
; __device__ __forceinline__ void kmma(f32x16& p0, f32x16& p1, const bf16x8 (&kf)[8], const bf16x8* qr) {
;   asm volatile("s_waitcnt lgkmcnt(0)" ::: "memory"); SBAR();
;   p0 = f32x16{}; p1 = f32x16{};
; #pragma unroll
;   for (int d0 = 0; d0 < 4; ++d0) { p0 = __builtin_amdgcn_mfma_f32_32x32x16_bf16(kf[2 * d0], qr[d0], p0, 0, 0, 0); p1 = __builtin_amdgcn_mfma_f32_32x32x16_bf16(kf[2 * d0 + 1], qr[d0], p1, 0, 0, 0); }
; }
; __device__ __forceinline__ void qkt(f32x16& p0, f32x16& p1, const char* Ks, const bf16x8* qr, int r32, int hi, int sb) {
;   bf16x8 kf[8]; kload(kf, Ks, r32, hi, sb); SBAR(); kmma(p0, p1, kf, qr);
; }
; __device__ __forceinline__ int v_st(int k, int c) { const int kk = (k & ~0xC) | ((k & 4) << 1) | ((k & 8) >> 1); return ((kk >> 3) * 4 + (c >> 5)) * 512 + ((kk & 7) * 32 + (c & 31)) * 2; }
; __device__ __forceinline__ int v_rd_base(int lane) { return ((lane & 3) << 3) | (((lane >> 2) & 3) << 6) | (((lane >> 4) & 1) << 5) | (((lane >> 5) & 1) << 8); }
; template <int OFF> __device__ __forceinline__ s16x4 tr_read(int vb) {
;   s16x4 r; asm volatile("ds_read_b64_tr_b16 %0, %1 offset:%2" : "=&v"(r) : "v"(vb), "i"(OFF) : "memory"); return r;
; }
; template <int D0> __device__ __forceinline__ void v_frag_read(VFrag& f, int vb) {
;   f.l0 = tr_read<v_rd_off(D0, 0, 0)>(vb); f.h0 = tr_read<v_rd_off(D0, 0, 1)>(vb); f.l1 = tr_read<v_rd_off(D0, 1, 0)>(vb); f.h1 = tr_read<v_rd_off(D0, 1, 1)>(vb);
.LBB0_770:
	s_and_b32 s0, s12, 0xff
	s_mulk_i32 s0, 0xab
	s_lshr_b32 s0, s0, 9
	s_mul_i32 s0, s0, 3
	s_sub_i32 s0, s12, s0
	s_and_b32 s0, s0, 0xff
	s_lshl_b32 s0, s0, 14
	s_add_i32 s0, s0, 0
	v_add_u32_e32 v86, s0, v169
	v_add_u32_e32 v90, s0, v170
	ds_read_b128 v[82:85], v86
	ds_read_b128 v[86:89], v86 offset:8192
	ds_read_b128 v[130:133], v90
	ds_read_b128 v[134:137], v90 offset:8192
	v_add_u32_e32 v90, s0, v171
	ds_read_b128 v[206:209], v90
	ds_read_b128 v[210:213], v90 offset:8192
	v_add_u32_e32 v90, s0, v172
	ds_read_b128 v[214:217], v90
	ds_read_b128 v[218:221], v90 offset:8192
	s_and_b32 s13, s36, 0xc000
	v_add_u32_e32 v244, s13, v164
	ds_read_b64_tr_b16 v[228:229], v244 offset:0
	ds_read_b64_tr_b16 v[230:231], v244 offset:0x800
	ds_read_b64_tr_b16 v[232:233], v244 offset:0x1000
	ds_read_b64_tr_b16 v[234:235], v244 offset:0x1800
	ds_read_b64_tr_b16 v[236:237], v244 offset:0x2000
	ds_read_b64_tr_b16 v[238:239], v244 offset:0x2800
	ds_read_b64_tr_b16 v[240:241], v244 offset:0x3000
	ds_read_b64_tr_b16 v[242:243], v244 offset:0x3800
	v_exp_f32_e32 v148, v66
	v_add_f32_e32 v66, 0, v175
	v_add_f32_e32 v66, v177, v66
	v_add_f32_e32 v66, v192, v66
	v_add_f32_e32 v66, v195, v66
	v_add_f32_e32 v66, v196, v66
	v_add_f32_e32 v66, v199, v66
	v_add_f32_e32 v66, v200, v66
	v_add_f32_e32 v66, v203, v66
	v_add_f32_e32 v66, v176, v66
	v_add_f32_e32 v66, v193, v66
	v_add_f32_e32 v66, v194, v66
	v_add_f32_e32 v66, v197, v66
	v_add_f32_e32 v66, v198, v66
	v_exp_f32_e32 v149, v67
	v_add_f32_e32 v66, v201, v66
	s_waitcnt lgkmcnt(15)
	v_mfma_f32_32x32x16_bf16 v[98:113], v[82:85], v[126:129], 0
	v_exp_f32_e32 v150, v68
	s_add_i32 s37, s12, 2
	v_add_f32_e32 v66, v202, v66
	s_cmpk_lt_u32 s12, 0x7e
	v_exp_f32_e32 v151, v69
	s_cselect_b64 s[0:1], -1, 0
	v_add_f32_e32 v66, v204, v66
	s_and_b64 s[10:11], s[0:1], exec
	s_cselect_b32 s10, 0, 0xffffff80
	s_waitcnt lgkmcnt(14)
	v_mfma_f32_32x32x16_bf16 v[82:97], v[86:89], v[126:129], 0
	v_exp_f32_e32 v186, v70
	s_add_i32 s58, s37, s10
	v_add_f32_e32 v66, v148, v66
	s_and_b64 s[0:1], s[0:1], exec
	v_exp_f32_e32 v187, v71
	s_cselect_b32 s1, s9, s30
	v_add_f32_e32 v66, v149, v66
	s_cselect_b32 s0, s8, s26
	v_exp_f32_e32 v188, v72
	s_lshl_b64 s[10:11], s[58:59], 17
	s_lshl_b64 s[0:1], s[0:1], 11
	s_waitcnt lgkmcnt(13)
	v_mfma_f32_32x32x16_bf16 v[98:113], v[130:133], v[122:125], v[98:113]
	v_add_f32_e32 v66, v150, v66
	s_add_u32 s10, s10, s0
	v_exp_f32_e32 v189, v73
	s_addc_u32 s11, s11, s1
	v_add_f32_e32 v66, v151, v66
	s_add_u32 s0, s20, s10
	v_exp_f32_e32 v205, v74
	s_addc_u32 s1, s21, s11
	s_add_u32 s10, s22, s10
	s_waitcnt lgkmcnt(12)
	v_mfma_f32_32x32x16_bf16 v[82:97], v[134:137], v[122:125], v[82:97]
	v_add_f32_e32 v66, v186, v66
	s_addc_u32 s11, s23, s11
	v_exp_f32_e32 v222, v75
	s_and_b32 s13, s37, 0xff
	v_add_f32_e32 v66, v187, v66
	s_mulk_i32 s13, 0xab
	v_exp_f32_e32 v223, v76
	s_lshr_b32 s13, s13, 9
	v_add_f32_e32 v66, v188, v66
	s_mul_i32 s13, s13, 3
	s_sub_i32 s13, s37, s13
	s_waitcnt lgkmcnt(11)
	v_mfma_f32_32x32x16_bf16 v[98:113], v[206:209], v[118:121], v[98:113]
	v_exp_f32_e32 v224, v77
	s_and_b32 s13, s13, 0xff
	v_add_f32_e32 v66, v189, v66
	s_lshl_b32 s13, s13, 14
	v_exp_f32_e32 v225, v78
	s_add_i32 s42, s36, 0xffffc000
	v_add_f32_e32 v66, v205, v66
	s_and_b32 s42, s42, 0xc000
	s_add_i32 s13, s13, s27
	s_waitcnt lgkmcnt(10)
	v_mfma_f32_32x32x16_bf16 v[82:97], v[210:213], v[118:121], v[82:97]
	v_exp_f32_e32 v226, v79
	s_add_i32 s42, s42, s31
	v_add_f32_e32 v66, v222, v66
	v_lshl_add_u64 v[246:247], s[0:1], 0, v[146:147]
	v_exp_f32_e32 v227, v80
	s_mov_b32 m0, s13
	v_add_f32_e32 v66, v223, v66
	s_nop 0
	v_exp_f32_e32 v81, v81
	global_load_lds_dwordx4 v[246:247], off
	v_lshl_add_u64 v[246:247], s[10:11], 0, v[142:143]
	s_waitcnt lgkmcnt(9)
	v_mfma_f32_32x32x16_bf16 v[98:113], v[214:217], v[114:117], v[98:113]
	v_add_f32_e32 v66, v224, v66
	s_mov_b32 m0, s42
	v_add_f32_e32 v66, v225, v66
	s_nop 0
	v_add_f32_e32 v66, v226, v66
	global_load_lds_dwordx4 v[246:247], off
	v_add_f32_e32 v66, v227, v66
	v_lshl_add_u64 v[246:247], s[0:1], 0, v[144:145]
	s_add_i32 m0, s13, 0x2000
	s_waitcnt lgkmcnt(8)
	v_mfma_f32_32x32x16_bf16 v[82:97], v[218:221], v[114:117], v[82:97]
	v_add_f32_e32 v130, v81, v66
	s_nop 0
	v_mov_b32_e32 v131, v130
	global_load_lds_dwordx4 v[246:247], off
	v_cvt_pk_bf16_f32 v66, v175, v177
	v_lshl_add_u64 v[246:247], s[10:11], 0, v[154:155]
	v_cvt_pk_bf16_f32 v67, v192, v195
	s_add_i32 m0, s42, 0x2000
	v_cvt_pk_bf16_f32 v68, v196, v199
	s_nop 0
	global_load_lds_dwordx4 v[246:247], off
	v_permlane32_swap_b32_e32 v130, v131
	v_cvt_pk_bf16_f32 v69, v200, v203
	v_permlane32_swap_b32_e32 v66, v68
	v_cvt_pk_bf16_f32 v70, v176, v193
	v_cvt_pk_bf16_f32 v71, v194, v197
	v_cvt_pk_bf16_f32 v72, v198, v201
	v_cvt_pk_bf16_f32 v73, v202, v204
	v_cvt_pk_bf16_f32 v74, v148, v149
	v_cvt_pk_bf16_f32 v75, v150, v151
	v_cvt_pk_bf16_f32 v76, v186, v187
	v_cvt_pk_bf16_f32 v77, v188, v189
	v_cvt_pk_bf16_f32 v78, v205, v222
	v_cvt_pk_bf16_f32 v79, v223, v224
	v_cvt_pk_bf16_f32 v80, v225, v226
	v_cvt_pk_bf16_f32 v81, v227, v81
	v_permlane32_swap_b32_e32 v67, v69
	v_permlane32_swap_b32_e32 v70, v72
	v_permlane32_swap_b32_e32 v71, v73
	v_permlane32_swap_b32_e32 v74, v76
	v_permlane32_swap_b32_e32 v75, v77
	v_permlane32_swap_b32_e32 v78, v80
	v_permlane32_swap_b32_e32 v79, v81
	ds_read_b64_tr_b16 v[204:205], v244 offset:0x200
	ds_read_b64_tr_b16 v[206:207], v244 offset:0xa00
	ds_read_b64_tr_b16 v[208:209], v244 offset:0x1200
	ds_read_b64_tr_b16 v[210:211], v244 offset:0x1a00
	ds_read_b64_tr_b16 v[212:213], v244 offset:0x2200
	ds_read_b64_tr_b16 v[214:215], v244 offset:0x2a00
	ds_read_b64_tr_b16 v[216:217], v244 offset:0x3200
	ds_read_b64_tr_b16 v[218:219], v244 offset:0x3a00
	s_waitcnt lgkmcnt(14)
; __device__ __forceinline__ void partialSM(f32x16& p0, f32x16& p1, float& m_reg, float& mn, float& alpha) {
;   constexpr float C = SCALE * 1.4426950408889634f;
;   float pmax = p0[0]; for (int r = 1; r < 16; ++r) pmax = fmaxf(pmax, p0[r]); for (int r = 0; r < 16; ++r) pmax = fmaxf(pmax, p1[r]);
;   { auto rr = __builtin_amdgcn_permlane32_swap(__float_as_uint(pmax), __float_as_uint(pmax), false, false);
;     pmax = fmaxf(__uint_as_float(rr[0]), __uint_as_float(rr[1])); }
;   if (__builtin_expect(__all(pmax - m_reg <= THR / SCALE), 1)) { mn = m_reg; alpha = 1.f; }
;   else { mn = fmaxf(m_reg, pmax); alpha = __builtin_amdgcn_exp2f((m_reg - mn) * C); m_reg = mn; }
;   float mnC = -mn * C;
;   for (int r = 0; r < 16; ++r) p0[r] = fmaf(p0[r], C, mnC); for (int r = 0; r < 16; ++r) p1[r] = fmaf(p1[r], C, mnC);
;   for (int r = 0; r < 16; ++r) p0[r] = __builtin_amdgcn_exp2f(p0[r]);
; }
; template <int D0> __device__ __forceinline__ void v_frag_read(VFrag& f, int vb) {
;   f.l0 = tr_read<v_rd_off(D0, 0, 0)>(vb); f.h0 = tr_read<v_rd_off(D0, 0, 1)>(vb); f.l1 = tr_read<v_rd_off(D0, 1, 0)>(vb); f.h1 = tr_read<v_rd_off(D0, 1, 1)>(vb);
;   f.l2 = tr_read<v_rd_off(D0, 2, 0)>(vb); f.h2 = tr_read<v_rd_off(D0, 2, 1)>(vb); f.l3 = tr_read<v_rd_off(D0, 3, 0)>(vb); f.h3 = tr_read<v_rd_off(D0, 3, 1)>(vb);
; }
; __device__ __forceinline__ void pv_mma(f32x16& od, const VFrag& f, bf16x8 pa0, bf16x8 pa1, bf16x8 pa2, bf16x8 pa3) {
;     ...
;   od = __builtin_amdgcn_mfma_f32_32x32x16_bf16(pa0, PK(f.l0, f.h0), od, 0, 0, 0);
;   od = __builtin_amdgcn_mfma_f32_32x32x16_bf16(pa1, PK(f.l1, f.h1), od, 0, 0, 0);
;   od = __builtin_amdgcn_mfma_f32_32x32x16_bf16(pa2, PK(f.l2, f.h2), od, 0, 0, 0);
;   od = __builtin_amdgcn_mfma_f32_32x32x16_bf16(pa3, PK(f.l3, f.h3), od, 0, 0, 0);
;     ...
; }
; __device__ __forceinline__ void pv_d0(f32x16* o, int vb, bf16x8 pa0, bf16x8 pa1, bf16x8 pa2, bf16x8 pa3) {
;   VFrag fa, fb;
;   v_frag_read<0>(fa, vb);
;   asm volatile("s_waitcnt lgkmcnt(0)" ::: "memory"); SBAR();
;   v_frag_read<1>(fb, vb); SBAR();
;   pv_mma(o[0], fa, pa0, pa1, pa2, pa3); SBAR();
;   asm volatile("s_waitcnt lgkmcnt(0)" ::: "memory"); SBAR();
;   v_frag_read<2>(fa, vb); SBAR();
;   pv_mma(o[1], fb, pa0, pa1, pa2, pa3); SBAR();
;   asm volatile("s_waitcnt lgkmcnt(0)" ::: "memory"); SBAR();
;   v_frag_read<3>(fb, vb); SBAR();
;   pv_mma(o[2], fa, pa0, pa1, pa2, pa3); SBAR();
	v_mfma_f32_32x32x16_bf16 v[18:33], v[66:69], v[228:231], v[18:33]
	v_max_f32_e32 v245, v99, v99
	v_max_f32_e32 v246, v98, v98
	v_max_f32_e32 v245, v246, v245
	v_max3_f32 v245, v245, v100, v101
	v_max3_f32 v245, v245, v102, v103
	v_max3_f32 v245, v245, v104, v105
	v_max3_f32 v245, v245, v106, v107
	v_max3_f32 v245, v245, v108, v109
	s_waitcnt lgkmcnt(12)
	v_mfma_f32_32x32x16_bf16 v[18:33], v[70:73], v[232:235], v[18:33]
	v_max3_f32 v245, v245, v110, v111
	v_max3_f32 v245, v245, v112, v113
	v_max3_f32 v245, v245, v82, v83
	v_max3_f32 v245, v245, v84, v85
	v_max3_f32 v245, v245, v86, v87
	v_max3_f32 v245, v245, v88, v89
	v_max3_f32 v245, v245, v90, v91
	v_max3_f32 v245, v245, v92, v93
	s_waitcnt lgkmcnt(10)
	v_mfma_f32_32x32x16_bf16 v[18:33], v[74:77], v[236:239], v[18:33]
	v_max3_f32 v245, v245, v94, v95
	v_max3_f32 v245, v245, v96, v97
	v_mov_b32_e32 v246, v245
	s_nop 1
	v_permlane32_swap_b32_e32 v245, v246
	v_max_f32_e32 v246, v246, v246
	v_max_f32_e32 v245, v245, v245
	v_max_f32_e32 v245, v245, v246
	v_sub_f32_e32 v246, v245, v174
	s_waitcnt lgkmcnt(8)
	v_mfma_f32_32x32x16_bf16 v[18:33], v[78:81], v[240:243], v[18:33]
	v_cmp_ge_f32_e32 vcc, s63, v246
	v_max_f32_e32 v246, v174, v174
	v_max_f32_e32 v245, v246, v245
	v_sub_f32_e32 v246, v174, v245
	v_mul_f32_e32 v246, 0x3e38aa3b, v246
	v_exp_f32_e32 v246, v246
	s_cmp_eq_u64 vcc, exec
	s_cselect_b64 s[0:1], -1, 0
	v_cndmask_b32_e64 v132, v246, 1.0, s[0:1]
	ds_read_b64_tr_b16 v[228:229], v244 offset:0x400
	ds_read_b64_tr_b16 v[230:231], v244 offset:0xc00
	ds_read_b64_tr_b16 v[232:233], v244 offset:0x1400
	ds_read_b64_tr_b16 v[234:235], v244 offset:0x1c00
	ds_read_b64_tr_b16 v[236:237], v244 offset:0x2400
	ds_read_b64_tr_b16 v[238:239], v244 offset:0x2c00
	ds_read_b64_tr_b16 v[240:241], v244 offset:0x3400
	ds_read_b64_tr_b16 v[242:243], v244 offset:0x3c00
	v_cndmask_b32_e64 v133, v245, v174, s[0:1]
	v_mul_f32_e32 v148, 0xbe38aa3b, v133
	s_waitcnt lgkmcnt(14)
	v_mfma_f32_32x32x16_bf16 v[50:65], v[66:69], v[204:207], v[50:65]
	v_fmamk_f32 v98, v98, 0x3e38aa3b, v148
	v_fmamk_f32 v99, v99, 0x3e38aa3b, v148
	v_fmamk_f32 v100, v100, 0x3e38aa3b, v148
	v_fmamk_f32 v101, v101, 0x3e38aa3b, v148
	s_waitcnt lgkmcnt(12)
	v_mfma_f32_32x32x16_bf16 v[50:65], v[70:73], v[208:211], v[50:65]
	v_fmamk_f32 v102, v102, 0x3e38aa3b, v148
	v_fmamk_f32 v103, v103, 0x3e38aa3b, v148
	v_fmamk_f32 v104, v104, 0x3e38aa3b, v148
	v_fmamk_f32 v105, v105, 0x3e38aa3b, v148
	s_waitcnt lgkmcnt(10)
	v_mfma_f32_32x32x16_bf16 v[50:65], v[74:77], v[212:215], v[50:65]
	v_fmamk_f32 v106, v106, 0x3e38aa3b, v148
	v_fmamk_f32 v107, v107, 0x3e38aa3b, v148
	v_fmamk_f32 v108, v108, 0x3e38aa3b, v148
	v_fmamk_f32 v109, v109, 0x3e38aa3b, v148
	s_waitcnt lgkmcnt(8)
	v_mfma_f32_32x32x16_bf16 v[50:65], v[78:81], v[216:219], v[50:65]
	v_fmamk_f32 v110, v110, 0x3e38aa3b, v148
	v_fmamk_f32 v111, v111, 0x3e38aa3b, v148
	v_fmamk_f32 v112, v112, 0x3e38aa3b, v148
	v_fmamk_f32 v113, v113, 0x3e38aa3b, v148
	ds_read_b64_tr_b16 v[204:205], v244 offset:0x600
	ds_read_b64_tr_b16 v[206:207], v244 offset:0xe00
	ds_read_b64_tr_b16 v[208:209], v244 offset:0x1600
	ds_read_b64_tr_b16 v[210:211], v244 offset:0x1e00
	ds_read_b64_tr_b16 v[212:213], v244 offset:0x2600
	ds_read_b64_tr_b16 v[214:215], v244 offset:0x2e00
	ds_read_b64_tr_b16 v[216:217], v244 offset:0x3600
	ds_read_b64_tr_b16 v[218:219], v244 offset:0x3e00
	s_waitcnt lgkmcnt(14)
	v_mfma_f32_32x32x16_bf16 v[34:49], v[66:69], v[228:231], v[34:49]
	v_fmamk_f32 v82, v82, 0x3e38aa3b, v148
	v_fmamk_f32 v83, v83, 0x3e38aa3b, v148
	v_fmamk_f32 v84, v84, 0x3e38aa3b, v148
	v_fmamk_f32 v85, v85, 0x3e38aa3b, v148
	s_waitcnt lgkmcnt(12)
	v_mfma_f32_32x32x16_bf16 v[34:49], v[70:73], v[232:235], v[34:49]
	v_fmamk_f32 v86, v86, 0x3e38aa3b, v148
	v_fmamk_f32 v87, v87, 0x3e38aa3b, v148
	s_add_i32 s13, s36, 0xffff4000
	v_fmamk_f32 v149, v88, 0x3e38aa3b, v148
	s_waitcnt lgkmcnt(10)
	v_mfma_f32_32x32x16_bf16 v[34:49], v[74:77], v[236:239], v[34:49]
	v_fmamk_f32 v150, v89, 0x3e38aa3b, v148
	v_fmamk_f32 v151, v90, 0x3e38aa3b, v148
	v_fmamk_f32 v186, v91, 0x3e38aa3b, v148
	v_fmamk_f32 v187, v92, 0x3e38aa3b, v148
	s_waitcnt lgkmcnt(8)
	v_mfma_f32_32x32x16_bf16 v[34:49], v[78:81], v[240:243], v[34:49]
	v_fmamk_f32 v188, v93, 0x3e38aa3b, v148
	v_fmamk_f32 v189, v94, 0x3e38aa3b, v148
	v_exp_f32_e32 v192, v98
	v_exp_f32_e32 v193, v99
	v_exp_f32_e32 v194, v100
	v_exp_f32_e32 v195, v101
	s_waitcnt lgkmcnt(6)
	v_mfma_f32_32x32x16_bf16 v[2:17], v[66:69], v[204:207], v[2:17]
	v_exp_f32_e32 v196, v102
	v_exp_f32_e32 v197, v103
	v_exp_f32_e32 v198, v104
	v_exp_f32_e32 v199, v105
	s_waitcnt lgkmcnt(4)
	v_mfma_f32_32x32x16_bf16 v[2:17], v[70:73], v[208:211], v[2:17]
	v_exp_f32_e32 v200, v106
	v_exp_f32_e32 v201, v107
	v_exp_f32_e32 v202, v108
	v_exp_f32_e32 v203, v109
	v_exp_f32_e32 v204, v110
	v_exp_f32_e32 v205, v111
	s_waitcnt lgkmcnt(2)
	v_mfma_f32_32x32x16_bf16 v[2:17], v[74:77], v[212:215], v[2:17]
	v_exp_f32_e32 v206, v112
	v_exp_f32_e32 v207, v113
	v_fmamk_f32 v208, v95, 0x3e38aa3b, v148
	v_fmamk_f32 v209, v96, 0x3e38aa3b, v148
	v_fmac_f32_e32 v148, 0x3e38aa3b, v97
	s_waitcnt lgkmcnt(0)
	v_mfma_f32_32x32x16_bf16 v[2:17], v[78:81], v[216:219], v[2:17]
	v_cmp_gt_f32_e32 vcc, 1.0, v132
	s_cbranch_vccz .LBB0_774
	s_and_saveexec_b64 s[10:11], s[40:41]
	ds_write_b32 v162, v132 offset:128
	s_or_b64 exec, exec, s[10:11]
	s_waitcnt lgkmcnt(0)
	v_add_u32_e32 v67, s18, v140
	ds_read_b128 v[68:71], v67 offset:224
	ds_read_b128 v[72:75], v67 offset:192
	ds_read_b128 v[76:79], v67 offset:160
	ds_read_b128 v[134:137], v67 offset:128
	s_waitcnt lgkmcnt(0)
	v_pk_mul_f32 v[30:31], v[30:31], v[68:69]
	v_pk_mul_f32 v[26:27], v[26:27], v[72:73]
	v_pk_mul_f32 v[22:23], v[22:23], v[76:77]
	v_pk_mul_f32 v[32:33], v[32:33], v[70:71]
	v_pk_mul_f32 v[28:29], v[28:29], v[74:75]
	v_pk_mul_f32 v[24:25], v[24:25], v[78:79]
	v_pk_mul_f32 v[20:21], v[20:21], v[136:137]
	v_pk_mul_f32 v[18:19], v[18:19], v[134:135]
	v_pk_mul_f32 v[62:63], v[62:63], v[68:69]
	v_pk_mul_f32 v[58:59], v[58:59], v[72:73]
	v_pk_mul_f32 v[54:55], v[54:55], v[76:77]
	v_pk_mul_f32 v[64:65], v[64:65], v[70:71]
	v_pk_mul_f32 v[60:61], v[60:61], v[74:75]
	v_pk_mul_f32 v[56:57], v[56:57], v[78:79]
	v_pk_mul_f32 v[52:53], v[52:53], v[136:137]
	v_pk_mul_f32 v[50:51], v[50:51], v[134:135]
	v_pk_mul_f32 v[46:47], v[46:47], v[68:69]
	v_pk_mul_f32 v[42:43], v[42:43], v[72:73]
	v_pk_mul_f32 v[38:39], v[38:39], v[76:77]
	v_pk_mul_f32 v[48:49], v[48:49], v[70:71]
	v_pk_mul_f32 v[44:45], v[44:45], v[74:75]
	v_pk_mul_f32 v[40:41], v[40:41], v[78:79]
	v_pk_mul_f32 v[36:37], v[36:37], v[136:137]
	v_pk_mul_f32 v[34:35], v[34:35], v[134:135]
	v_pk_mul_f32 v[14:15], v[14:15], v[68:69]
	v_pk_mul_f32 v[10:11], v[10:11], v[72:73]
	v_pk_mul_f32 v[6:7], v[6:7], v[76:77]
	v_pk_mul_f32 v[16:17], v[16:17], v[70:71]
	v_pk_mul_f32 v[12:13], v[12:13], v[74:75]
	v_pk_mul_f32 v[8:9], v[8:9], v[78:79]
	v_pk_mul_f32 v[4:5], v[4:5], v[136:137]
	v_pk_mul_f32 v[2:3], v[2:3], v[134:135]
; #define SBAR() __builtin_amdgcn_sched_barrier(0)
; __device__ __forceinline__ void finishSM(f32x16& p0, f32x16& p1, float alpha, float& l_reg, bf16x8& pa0, bf16x8& pa1, bf16x8& pa2, bf16x8& pa3) {
;   for (int r = 0; r < 16; ++r) p1[r] = __builtin_amdgcn_exp2f(p1[r]);
;   float ps = 0; for (int r = 0; r < 16; ++r) ps += p0[r]; for (int r = 0; r < 16; ++r) ps += p1[r];
;   { auto rr = __builtin_amdgcn_permlane32_swap(__float_as_uint(ps), __float_as_uint(ps), false, false);
;     ps = __uint_as_float(rr[0]) + __uint_as_float(rr[1]); }
;   l_reg = l_reg * alpha + ps;
;     ...
;   PK4(p0, 0, pa0); PK4(p0, 8, pa1); PK4(p1, 0, pa2); PK4(p1, 8, pa3);
;     ...
; }
; __device__ __forceinline__ void kload(bf16x8 (&kf)[8], const char* Ks, int r32, int hi, int sb) {
; #pragma unroll
;   for (int d0 = 0; d0 < 4; ++d0) { const int cb = sb + (d0 * 16 + hi * 8) * 2;
;     kf[2 * d0] = *reinterpret_cast<const bf16x8*>(Ks + KSWZ(r32, cb)); kf[2 * d0 + 1] = *reinterpret_cast<const bf16x8*>(Ks + KSWZ(32 + r32, cb)); }
; }
; __device__ __forceinline__ void kmma(f32x16& p0, f32x16& p1, const bf16x8 (&kf)[8], const bf16x8* qr) {
;   asm volatile("s_waitcnt lgkmcnt(0)" ::: "memory"); SBAR();
;   p0 = f32x16{}; p1 = f32x16{};
; #pragma unroll
;   for (int d0 = 0; d0 < 4; ++d0) { p0 = __builtin_amdgcn_mfma_f32_32x32x16_bf16(kf[2 * d0], qr[d0], p0, 0, 0, 0); p1 = __builtin_amdgcn_mfma_f32_32x32x16_bf16(kf[2 * d0 + 1], qr[d0], p1, 0, 0, 0); }
; }
; __device__ __forceinline__ void qkt(f32x16& p0, f32x16& p1, const char* Ks, const bf16x8* qr, int r32, int hi, int sb) {
;   bf16x8 kf[8]; kload(kf, Ks, r32, hi, sb); SBAR(); kmma(p0, p1, kf, qr);
; }
.LBB0_774:
	s_waitcnt vmcnt(4)
	s_barrier
	s_and_b32 s46, s13, 0xc000
	v_add_u32_e32 v244, s46, v164
	s_add_i32 s0, s12, 1
	s_mul_i32 s1, s0, 0xab
	s_bfe_u32 s1, s1, 0x70009
	s_mul_i32 s1, s1, 3
	s_sub_i32 s0, s0, s1
	s_and_b32 s0, s0, 0xff
	s_lshl_b32 s0, s0, 14
	s_add_i32 s0, s0, 0
	v_add_u32_e32 v70, s0, v169
	v_add_u32_e32 v74, s0, v170
	ds_read_b128 v[66:69], v70
	ds_read_b128 v[70:73], v70 offset:8192
	ds_read_b128 v[98:101], v74
	ds_read_b128 v[102:105], v74 offset:8192
	v_add_u32_e32 v74, s0, v171
	ds_read_b128 v[106:109], v74
	ds_read_b128 v[110:113], v74 offset:8192
	v_add_u32_e32 v74, s0, v172
	ds_read_b128 v[134:137], v74
	ds_read_b128 v[174:177], v74 offset:8192
	ds_read_b64_tr_b16 v[228:229], v244 offset:0
	ds_read_b64_tr_b16 v[230:231], v244 offset:0x800
	ds_read_b64_tr_b16 v[232:233], v244 offset:0x1000
	ds_read_b64_tr_b16 v[234:235], v244 offset:0x1800
	ds_read_b64_tr_b16 v[236:237], v244 offset:0x2000
	ds_read_b64_tr_b16 v[238:239], v244 offset:0x2800
	ds_read_b64_tr_b16 v[240:241], v244 offset:0x3000
	ds_read_b64_tr_b16 v[242:243], v244 offset:0x3800
	v_exp_f32_e32 v210, v82
	v_exp_f32_e32 v211, v83
	v_exp_f32_e32 v212, v84
	v_exp_f32_e32 v213, v85
	v_exp_f32_e32 v214, v86
	v_exp_f32_e32 v215, v87
	v_add_f32_e32 v216, 0, v192
	v_add_f32_e32 v216, v193, v216
	v_add_f32_e32 v216, v194, v216
	v_add_f32_e32 v216, v195, v216
	v_exp_f32_e32 v149, v149
	v_exp_f32_e32 v150, v150
	v_exp_f32_e32 v151, v151
	v_exp_f32_e32 v186, v186
	v_exp_f32_e32 v187, v187
	v_exp_f32_e32 v188, v188
	s_waitcnt lgkmcnt(15)
	v_mfma_f32_32x32x16_bf16 v[82:97], v[66:69], v[126:129], 0
	v_exp_f32_e32 v189, v189
	s_add_i32 s46, s12, 3
	v_exp_f32_e32 v208, v208
	s_cmpk_lt_u32 s12, 0x7d
	v_exp_f32_e32 v209, v209
	s_cselect_b64 s[42:43], -1, 0
	v_exp_f32_e32 v148, v148
	s_waitcnt lgkmcnt(14)
	v_mfma_f32_32x32x16_bf16 v[66:81], v[70:73], v[126:129], 0
	v_add_f32_e32 v248, v196, v216
	s_and_b64 s[44:45], s[42:43], exec
	v_add_f32_e32 v248, v197, v248
	s_cselect_b32 s44, 0, 0xffffff80
	v_add_f32_e32 v248, v198, v248
	s_add_i32 s58, s46, s44
	v_add_f32_e32 v248, v199, v248
	s_and_b64 s[42:43], s[42:43], exec
	v_add_f32_e32 v248, v200, v248
	s_waitcnt lgkmcnt(13)
	v_mfma_f32_32x32x16_bf16 v[82:97], v[98:101], v[122:125], v[82:97]
	v_add_f32_e32 v248, v201, v248
	s_cselect_b32 s43, s9, s30
	v_add_f32_e32 v248, v202, v248
	s_cselect_b32 s42, s8, s26
	v_add_f32_e32 v248, v203, v248
	s_lshl_b64 s[44:45], s[58:59], 17
	v_add_f32_e32 v248, v204, v248
	s_lshl_b64 s[42:43], s[42:43], 11
	s_waitcnt lgkmcnt(12)
	v_mfma_f32_32x32x16_bf16 v[66:81], v[102:105], v[122:125], v[66:81]
	v_add_f32_e32 v248, v205, v248
	s_add_u32 s44, s44, s42
	v_add_f32_e32 v248, v206, v248
	s_addc_u32 s45, s45, s43
	v_add_f32_e32 v248, v207, v248
	s_add_u32 s42, s20, s44
	v_add_f32_e32 v248, v210, v248
	v_add_f32_e32 v248, v211, v248
	s_waitcnt lgkmcnt(11)
	v_mfma_f32_32x32x16_bf16 v[82:97], v[106:109], v[118:121], v[82:97]
	v_add_f32_e32 v248, v212, v248
	s_addc_u32 s43, s21, s45
	v_add_f32_e32 v248, v213, v248
	s_add_u32 s44, s22, s44
	v_add_f32_e32 v248, v214, v248
	s_mul_i32 s47, s46, 0xab
	v_add_f32_e32 v248, v215, v248
	s_addc_u32 s45, s23, s45
	s_waitcnt lgkmcnt(10)
	v_mfma_f32_32x32x16_bf16 v[66:81], v[110:113], v[118:121], v[66:81]
	v_add_f32_e32 v248, v149, v248
	s_bfe_u32 s47, s47, 0x70009
	v_add_f32_e32 v248, v150, v248
	s_mul_i32 s47, s47, 3
	v_add_f32_e32 v248, v151, v248
	s_sub_i32 s46, s46, s47
	v_add_f32_e32 v248, v186, v248
	s_and_b32 s46, s46, 0xff
	v_add_f32_e32 v248, v187, v248
	s_waitcnt lgkmcnt(9)
	v_mfma_f32_32x32x16_bf16 v[82:97], v[134:137], v[114:117], v[82:97]
	v_add_f32_e32 v248, v188, v248
	s_lshl_b32 s46, s46, 14
	v_add_f32_e32 v248, v189, v248
	s_add_i32 s46, s46, s27
	v_add_f32_e32 v248, v208, v248
	s_and_b32 s47, s36, 0xc000
	v_add_f32_e32 v248, v209, v248
	s_add_i32 s47, s47, s31
	v_add_f32_e32 v99, v148, v248
	s_cmpk_gt_u32 s12, 0x80
	s_cselect_b64 s[10:11], -1, 0
	s_and_b64 vcc, exec, s[10:11]
	s_cbranch_vccnz .LBB0_776
	v_lshl_add_u64 v[246:247], s[42:43], 0, v[146:147]
	s_mov_b32 m0, s46
	s_nop 0
	global_load_lds_dwordx4 v[246:247], off
	v_lshl_add_u64 v[246:247], s[44:45], 0, v[142:143]
	s_mov_b32 m0, s47
	s_nop 0
	global_load_lds_dwordx4 v[246:247], off
	v_lshl_add_u64 v[246:247], s[42:43], 0, v[144:145]
	s_add_i32 m0, s46, 0x2000
	s_nop 0
	global_load_lds_dwordx4 v[246:247], off
	v_lshl_add_u64 v[246:247], s[44:45], 0, v[154:155]
	s_add_i32 m0, s47, 0x2000
	s_nop 0
	global_load_lds_dwordx4 v[246:247], off
; __device__ __forceinline__ void partialSM(f32x16& p0, f32x16& p1, float& m_reg, float& mn, float& alpha) {
;   constexpr float C = SCALE * 1.4426950408889634f;
;   float pmax = p0[0]; for (int r = 1; r < 16; ++r) pmax = fmaxf(pmax, p0[r]); for (int r = 0; r < 16; ++r) pmax = fmaxf(pmax, p1[r]);
;   { auto rr = __builtin_amdgcn_permlane32_swap(__float_as_uint(pmax), __float_as_uint(pmax), false, false);
;     pmax = fmaxf(__uint_as_float(rr[0]), __uint_as_float(rr[1])); }
;   if (__builtin_expect(__all(pmax - m_reg <= THR / SCALE), 1)) { mn = m_reg; alpha = 1.f; }
;   else { mn = fmaxf(m_reg, pmax); alpha = __builtin_amdgcn_exp2f((m_reg - mn) * C); m_reg = mn; }
;   float mnC = -mn * C;
;   for (int r = 0; r < 16; ++r) p0[r] = fmaf(p0[r], C, mnC); for (int r = 0; r < 16; ++r) p1[r] = fmaf(p1[r], C, mnC);
;   for (int r = 0; r < 16; ++r) p0[r] = __builtin_amdgcn_exp2f(p0[r]);
; }
; __device__ __forceinline__ void finishSM(f32x16& p0, f32x16& p1, float alpha, float& l_reg, bf16x8& pa0, bf16x8& pa1, bf16x8& pa2, bf16x8& pa3) {
;   for (int r = 0; r < 16; ++r) p1[r] = __builtin_amdgcn_exp2f(p1[r]);
;   float ps = 0; for (int r = 0; r < 16; ++r) ps += p0[r]; for (int r = 0; r < 16; ++r) ps += p1[r];
;   { auto rr = __builtin_amdgcn_permlane32_swap(__float_as_uint(ps), __float_as_uint(ps), false, false);
;     ps = __uint_as_float(rr[0]) + __uint_as_float(rr[1]); }
;   l_reg = l_reg * alpha + ps;
;     ...
;   PK4(p0, 0, pa0); PK4(p0, 8, pa1); PK4(p1, 0, pa2); PK4(p1, 8, pa3);
;     ...
; }
; template <int D0> __device__ __forceinline__ void v_frag_read(VFrag& f, int vb) {
;   f.l0 = tr_read<v_rd_off(D0, 0, 0)>(vb); f.h0 = tr_read<v_rd_off(D0, 0, 1)>(vb); f.l1 = tr_read<v_rd_off(D0, 1, 0)>(vb); f.h1 = tr_read<v_rd_off(D0, 1, 1)>(vb);
;   f.l2 = tr_read<v_rd_off(D0, 2, 0)>(vb); f.h2 = tr_read<v_rd_off(D0, 2, 1)>(vb); f.l3 = tr_read<v_rd_off(D0, 3, 0)>(vb); f.h3 = tr_read<v_rd_off(D0, 3, 1)>(vb);
; }
; __device__ __forceinline__ void pv_mma(f32x16& od, const VFrag& f, bf16x8 pa0, bf16x8 pa1, bf16x8 pa2, bf16x8 pa3) {
;     ...
;   od = __builtin_amdgcn_mfma_f32_32x32x16_bf16(pa0, PK(f.l0, f.h0), od, 0, 0, 0);
;   od = __builtin_amdgcn_mfma_f32_32x32x16_bf16(pa1, PK(f.l1, f.h1), od, 0, 0, 0);
;   od = __builtin_amdgcn_mfma_f32_32x32x16_bf16(pa2, PK(f.l2, f.h2), od, 0, 0, 0);
;   od = __builtin_amdgcn_mfma_f32_32x32x16_bf16(pa3, PK(f.l3, f.h3), od, 0, 0, 0);
;     ...
; }
.LBB0_776:
	v_mov_b32_e32 v100, v99
	s_nop 1
	v_permlane32_swap_b32_e32 v99, v100
	v_cvt_pk_bf16_f32 v102, v192, v193
	v_cvt_pk_bf16_f32 v103, v194, v195
	v_cvt_pk_bf16_f32 v104, v196, v197
	v_cvt_pk_bf16_f32 v105, v198, v199
	s_waitcnt lgkmcnt(8)
	v_mfma_f32_32x32x16_bf16 v[66:81], v[174:177], v[114:117], v[66:81]
	v_cvt_pk_bf16_f32 v106, v200, v201
	v_cvt_pk_bf16_f32 v107, v202, v203
	v_cvt_pk_bf16_f32 v108, v204, v205
	v_cvt_pk_bf16_f32 v109, v206, v207
	v_cvt_pk_bf16_f32 v110, v210, v211
	v_cvt_pk_bf16_f32 v111, v212, v213
	v_cvt_pk_bf16_f32 v112, v214, v215
	v_cvt_pk_bf16_f32 v113, v149, v150
	v_cvt_pk_bf16_f32 v134, v151, v186
	v_cvt_pk_bf16_f32 v135, v187, v188
	v_cvt_pk_bf16_f32 v136, v189, v208
	v_cvt_pk_bf16_f32 v137, v209, v148
	v_permlane32_swap_b32_e32 v102, v104
	v_permlane32_swap_b32_e32 v103, v105
	v_permlane32_swap_b32_e32 v106, v108
	v_permlane32_swap_b32_e32 v107, v109
	v_permlane32_swap_b32_e32 v110, v112
	v_permlane32_swap_b32_e32 v111, v113
	v_permlane32_swap_b32_e32 v134, v136
	v_permlane32_swap_b32_e32 v135, v137
	ds_read_b64_tr_b16 v[204:205], v244 offset:0x200
	ds_read_b64_tr_b16 v[206:207], v244 offset:0xa00
	ds_read_b64_tr_b16 v[208:209], v244 offset:0x1200
	ds_read_b64_tr_b16 v[210:211], v244 offset:0x1a00
	ds_read_b64_tr_b16 v[212:213], v244 offset:0x2200
	ds_read_b64_tr_b16 v[214:215], v244 offset:0x2a00
	ds_read_b64_tr_b16 v[216:217], v244 offset:0x3200
	ds_read_b64_tr_b16 v[218:219], v244 offset:0x3a00
	s_waitcnt lgkmcnt(14)
	v_mfma_f32_32x32x16_bf16 v[18:33], v[102:105], v[228:231], v[18:33]
	v_max_f32_e32 v245, v83, v83
	v_max_f32_e32 v246, v82, v82
	v_max_f32_e32 v245, v246, v245
	v_max3_f32 v245, v245, v84, v85
	v_max3_f32 v245, v245, v86, v87
	v_max3_f32 v245, v245, v88, v89
	v_max3_f32 v245, v245, v90, v91
	v_max3_f32 v245, v245, v92, v93
	s_waitcnt lgkmcnt(12)
	v_mfma_f32_32x32x16_bf16 v[18:33], v[106:109], v[232:235], v[18:33]
	v_max3_f32 v245, v245, v94, v95
	v_max3_f32 v245, v245, v96, v97
	v_max3_f32 v245, v245, v66, v67
	v_max3_f32 v245, v245, v68, v69
	v_max3_f32 v245, v245, v70, v71
	v_max3_f32 v245, v245, v72, v73
	v_max3_f32 v245, v245, v74, v75
	v_max3_f32 v245, v245, v76, v77
	s_waitcnt lgkmcnt(10)
	v_mfma_f32_32x32x16_bf16 v[18:33], v[110:113], v[236:239], v[18:33]
	v_max3_f32 v245, v245, v78, v79
	v_max3_f32 v245, v245, v80, v81
	v_mov_b32_e32 v246, v245
	s_nop 1
	v_permlane32_swap_b32_e32 v245, v246
	v_max_f32_e32 v246, v246, v246
	v_max_f32_e32 v245, v245, v245
	v_max_f32_e32 v245, v245, v246
	v_sub_f32_e32 v246, v245, v133
	s_waitcnt lgkmcnt(8)
	v_mfma_f32_32x32x16_bf16 v[18:33], v[134:137], v[240:243], v[18:33]
	v_cmp_ge_f32_e32 vcc, s63, v246
	v_max_f32_e32 v246, v133, v133
	v_max_f32_e32 v245, v246, v245
	v_sub_f32_e32 v246, v133, v245
	v_mul_f32_e32 v246, 0x3e38aa3b, v246
	v_exp_f32_e32 v246, v246
	s_cmp_eq_u64 vcc, exec
	s_cselect_b64 s[0:1], -1, 0
	v_cndmask_b32_e64 v247, v246, 1.0, s[0:1]
	ds_read_b64_tr_b16 v[228:229], v244 offset:0x400
	ds_read_b64_tr_b16 v[230:231], v244 offset:0xc00
	ds_read_b64_tr_b16 v[232:233], v244 offset:0x1400
	ds_read_b64_tr_b16 v[234:235], v244 offset:0x1c00
	ds_read_b64_tr_b16 v[236:237], v244 offset:0x2400
	ds_read_b64_tr_b16 v[238:239], v244 offset:0x2c00
	ds_read_b64_tr_b16 v[240:241], v244 offset:0x3400
	ds_read_b64_tr_b16 v[242:243], v244 offset:0x3c00
	v_cndmask_b32_e64 v174, v245, v133, s[0:1]
	v_mul_f32_e32 v98, 0xbe38aa3b, v174
	s_waitcnt lgkmcnt(14)
	v_mfma_f32_32x32x16_bf16 v[50:65], v[102:105], v[204:207], v[50:65]
	v_fmamk_f32 v82, v82, 0x3e38aa3b, v98
	v_fmamk_f32 v83, v83, 0x3e38aa3b, v98
	v_fmamk_f32 v84, v84, 0x3e38aa3b, v98
	v_fmamk_f32 v85, v85, 0x3e38aa3b, v98
	s_waitcnt lgkmcnt(12)
	v_mfma_f32_32x32x16_bf16 v[50:65], v[106:109], v[208:211], v[50:65]
	v_fmamk_f32 v86, v86, 0x3e38aa3b, v98
	v_fmamk_f32 v87, v87, 0x3e38aa3b, v98
	v_fmamk_f32 v88, v88, 0x3e38aa3b, v98
	v_fmamk_f32 v89, v89, 0x3e38aa3b, v98
	s_waitcnt lgkmcnt(10)
	v_mfma_f32_32x32x16_bf16 v[50:65], v[110:113], v[212:215], v[50:65]
	v_fmamk_f32 v90, v90, 0x3e38aa3b, v98
	v_fmamk_f32 v91, v91, 0x3e38aa3b, v98
	v_fmamk_f32 v92, v92, 0x3e38aa3b, v98
	v_fmamk_f32 v93, v93, 0x3e38aa3b, v98
	s_waitcnt lgkmcnt(8)
	v_mfma_f32_32x32x16_bf16 v[50:65], v[134:137], v[216:219], v[50:65]
	v_fmamk_f32 v94, v94, 0x3e38aa3b, v98
	v_fmamk_f32 v95, v95, 0x3e38aa3b, v98
	v_fmamk_f32 v96, v96, 0x3e38aa3b, v98
	v_fmamk_f32 v97, v97, 0x3e38aa3b, v98
	ds_read_b64_tr_b16 v[204:205], v244 offset:0x600
	ds_read_b64_tr_b16 v[206:207], v244 offset:0xe00
	ds_read_b64_tr_b16 v[208:209], v244 offset:0x1600
	ds_read_b64_tr_b16 v[210:211], v244 offset:0x1e00
	ds_read_b64_tr_b16 v[212:213], v244 offset:0x2600
	ds_read_b64_tr_b16 v[214:215], v244 offset:0x2e00
	ds_read_b64_tr_b16 v[216:217], v244 offset:0x3600
	ds_read_b64_tr_b16 v[218:219], v244 offset:0x3e00
	s_waitcnt lgkmcnt(14)
	v_mfma_f32_32x32x16_bf16 v[34:49], v[102:105], v[228:231], v[34:49]
	s_mov_b32 s46, 0x3e38aa3b
	v_pk_fma_f32 v[80:81], v[80:81], s[46:47], v[98:99] op_sel_hi:[1,0,0]
	v_pk_fma_f32 v[78:79], v[78:79], s[46:47], v[98:99] op_sel_hi:[1,0,0]
	s_waitcnt lgkmcnt(12)
	v_mfma_f32_32x32x16_bf16 v[34:49], v[106:109], v[232:235], v[34:49]
	v_pk_fma_f32 v[76:77], v[76:77], s[46:47], v[98:99] op_sel_hi:[1,0,0]
	v_pk_fma_f32 v[74:75], v[74:75], s[46:47], v[98:99] op_sel_hi:[1,0,0]
	v_pk_fma_f32 v[72:73], v[72:73], s[46:47], v[98:99] op_sel_hi:[1,0,0]
	s_waitcnt lgkmcnt(10)
	v_mfma_f32_32x32x16_bf16 v[34:49], v[110:113], v[236:239], v[34:49]
	v_pk_fma_f32 v[70:71], v[70:71], s[46:47], v[98:99] op_sel_hi:[1,0,0]
	v_pk_fma_f32 v[68:69], v[68:69], s[46:47], v[98:99] op_sel_hi:[1,0,0]
	v_pk_fma_f32 v[66:67], v[66:67], s[46:47], v[98:99] op_sel_hi:[1,0,0]
	s_waitcnt lgkmcnt(8)
	v_mfma_f32_32x32x16_bf16 v[34:49], v[134:137], v[240:243], v[34:49]
	v_exp_f32_e32 v175, v82
	v_exp_f32_e32 v177, v83
	v_exp_f32_e32 v192, v84
	s_waitcnt lgkmcnt(6)
	v_mfma_f32_32x32x16_bf16 v[2:17], v[102:105], v[204:207], v[2:17]
	v_mov_b32_e32 v205, v247
	v_exp_f32_e32 v204, v97
	v_exp_f32_e32 v195, v85
	v_exp_f32_e32 v196, v86
	v_exp_f32_e32 v199, v87
	v_exp_f32_e32 v200, v88
	s_waitcnt lgkmcnt(4)
	v_mfma_f32_32x32x16_bf16 v[2:17], v[106:109], v[208:211], v[2:17]
	v_exp_f32_e32 v203, v89
	v_exp_f32_e32 v176, v90
	v_exp_f32_e32 v193, v91
	v_exp_f32_e32 v194, v92
	s_waitcnt lgkmcnt(2)
	v_mfma_f32_32x32x16_bf16 v[2:17], v[110:113], v[212:215], v[2:17]
	v_exp_f32_e32 v197, v93
	v_exp_f32_e32 v198, v94
	v_exp_f32_e32 v201, v95
	v_exp_f32_e32 v202, v96
	s_waitcnt lgkmcnt(0)
	v_mfma_f32_32x32x16_bf16 v[2:17], v[134:137], v[216:219], v[2:17]
	v_cmp_gt_f32_e32 vcc, 1.0, v205
	s_cbranch_vccz .LBB0_780
; #define TILE_BAR(n) do { asm volatile("s_waitcnt vmcnt(" #n ")" ::: "memory"); __builtin_amdgcn_s_barrier(); asm volatile("" ::: "memory"); } while (0)
; __device__ __forceinline__ void attn_unit(const bf16* __restrict__ Qb, const bf16* __restrict__ Kh, const bf16* __restrict__ Vh, int klat0, int nlt, int kctx0, int NT,
;                                           float lam, float post, const float* __restrict__ subw, bf16* __restrict__ Ob, char* lds) {
;     ...
;       if (j + 3 < NT) TILE_BAR(4); else TILE_BAR(0);
	s_and_saveexec_b64 s[12:13], s[40:41]
	ds_write_b32 v162, v205 offset:128
	s_or_b64 exec, exec, s[12:13]
	s_waitcnt lgkmcnt(0)
	v_add_u32_e32 v101, s18, v140
	ds_read_b128 v[102:105], v101 offset:224
	ds_read_b128 v[106:109], v101 offset:192
	ds_read_b128 v[110:113], v101 offset:160
	ds_read_b128 v[134:137], v101 offset:128
	s_waitcnt lgkmcnt(0)
	v_pk_mul_f32 v[30:31], v[30:31], v[102:103]
	v_pk_mul_f32 v[26:27], v[26:27], v[106:107]
	v_pk_mul_f32 v[22:23], v[22:23], v[110:111]
	v_pk_mul_f32 v[32:33], v[32:33], v[104:105]
	v_pk_mul_f32 v[28:29], v[28:29], v[108:109]
	v_pk_mul_f32 v[24:25], v[24:25], v[112:113]
	v_pk_mul_f32 v[20:21], v[20:21], v[136:137]
	v_pk_mul_f32 v[18:19], v[18:19], v[134:135]
	v_pk_mul_f32 v[62:63], v[62:63], v[102:103]
	v_pk_mul_f32 v[58:59], v[58:59], v[106:107]
	v_pk_mul_f32 v[54:55], v[54:55], v[110:111]
	v_pk_mul_f32 v[64:65], v[64:65], v[104:105]
	v_pk_mul_f32 v[60:61], v[60:61], v[108:109]
	v_pk_mul_f32 v[56:57], v[56:57], v[112:113]
	v_pk_mul_f32 v[52:53], v[52:53], v[136:137]
	v_pk_mul_f32 v[50:51], v[50:51], v[134:135]
	v_pk_mul_f32 v[46:47], v[46:47], v[102:103]
	v_pk_mul_f32 v[42:43], v[42:43], v[106:107]
	v_pk_mul_f32 v[38:39], v[38:39], v[110:111]
	v_pk_mul_f32 v[48:49], v[48:49], v[104:105]
	v_pk_mul_f32 v[44:45], v[44:45], v[108:109]
	v_pk_mul_f32 v[40:41], v[40:41], v[112:113]
	v_pk_mul_f32 v[36:37], v[36:37], v[136:137]
	v_pk_mul_f32 v[34:35], v[34:35], v[134:135]
	v_pk_mul_f32 v[14:15], v[14:15], v[102:103]
	v_pk_mul_f32 v[10:11], v[10:11], v[106:107]
	v_pk_mul_f32 v[6:7], v[6:7], v[110:111]
	v_pk_mul_f32 v[16:17], v[16:17], v[104:105]
	v_pk_mul_f32 v[12:13], v[12:13], v[108:109]
	v_pk_mul_f32 v[8:9], v[8:9], v[112:113]
	v_pk_mul_f32 v[4:5], v[4:5], v[136:137]
	v_pk_mul_f32 v[2:3], v[2:3], v[134:135]
.LBB0_780:
	s_mov_b64 s[0:1], -1
	s_and_b64 vcc, exec, s[10:11]
	s_cbranch_vccz .LBB0_782
	s_waitcnt vmcnt(0)
	s_barrier
	s_mov_b64 s[0:1], 0

; __device__ __forceinline__ void partialSM(f32x16& p0, f32x16& p1, float& m_reg, float& mn, float& alpha) {
;     ...
;   for (int r = 0; r < 16; ++r) p0[r] = fmaf(p0[r], C, mnC); for (int r = 0; r < 16; ++r) p1[r] = fmaf(p1[r], C, mnC);
;   for (int r = 0; r < 16; ++r) p0[r] = __builtin_amdgcn_exp2f(p0[r]);
; }
; __device__ __forceinline__ void finishSM(f32x16& p0, f32x16& p1, float alpha, float& l_reg, bf16x8& pa0, bf16x8& pa1, bf16x8& pa2, bf16x8& pa3) {
;   for (int r = 0; r < 16; ++r) p1[r] = __builtin_amdgcn_exp2f(p1[r]);
;   float ps = 0; for (int r = 0; r < 16; ++r) ps += p0[r]; for (int r = 0; r < 16; ++r) ps += p1[r];
;   { auto rr = __builtin_amdgcn_permlane32_swap(__float_as_uint(ps), __float_as_uint(ps), false, false);
;     ps = __uint_as_float(rr[0]) + __uint_as_float(rr[1]); }
;   l_reg = l_reg * alpha + ps;
.LBB0_784:
	v_add_f32_e32 v82, v130, v131
	v_fmac_f32_e32 v82, v173, v163
	v_add_f32_e32 v163, v99, v100
	v_fmac_f32_e32 v163, v82, v132
	s_add_i32 s36, s36, 0x8000
	s_and_b64 vcc, exec, s[10:11]
	s_cbranch_vccnz .LBB0_786
	s_mov_b32 s12, s37
	v_mov_b32_e32 v173, v205
	s_branch .LBB0_770
